# v23: + qkprep quad exchanges via DPP, prenorm gate reductions via DPP transpose-reduce + permlane swaps (was 96 ds_bpermute round trips per row)
# speedup vs baseline: 1.0858x; 1.0132x over previous
.LBB0_173:
	s_andn2_saveexec_b64 s[10:11], s[10:11]
	v_ashrrev_i32_e32 v9, 31, v8
	v_lshlrev_b64 v[2:3], 20, v[4:5]
	v_lshl_add_u64 v[2:3], s[84:85], 0, v[2:3]
	v_lshlrev_b64 v[4:5], 12, v[8:9]
	v_lshl_add_u64 v[6:7], v[2:3], 0, v[4:5]
	v_mov_b64_e32 v[2:3], 0x3000
	s_or_b64 exec, exec, s[10:11]
	v_mov_b32_e32 v35, v0
	v_lshl_add_u64 v[4:5], v[6:7], 0, v[34:35]
	s_waitcnt vmcnt(1)
	v_mov_b32_e32 v6, v100
	v_mov_b32_e32 v7, v101
	v_mov_b32_e32 v8, v102
	v_mov_b32_e32 v9, v103
	v_mov_b32_e32 v12, v104
	v_mov_b32_e32 v13, v105
	v_mov_b32_e32 v14, v106
	v_mov_b32_e32 v15, v107
	v_lshl_add_u64 v[2:3], v[2:3], 2, s[86:87]
	s_mov_b64 s[10:11], 0x1000
	v_lshl_add_u64 v[44:45], v[2:3], 0, v[34:35]
	s_mov_b32 s6, 0x6400000
	v_mov_b32_e32 v37, v0
	v_mov_b32_e32 v39, v0
	v_mov_b32_e32 v41, v0
	v_mov_b32_e32 v16, v7
	v_mov_b32_e32 v17, v13
	v_mov_b32_e32 v10, v6
	v_mov_b32_e32 v11, v12
	v_pk_mul_f32 v[16:17], v[16:17], v[16:17]
	s_nop 0
	v_pk_fma_f32 v[10:11], v[10:11], v[10:11], v[16:17]
	v_mov_b32_e32 v16, v8
	v_mov_b32_e32 v17, v14
	v_pk_fma_f32 v[10:11], v[16:17], v[16:17], v[10:11]
	v_mov_b32_e32 v16, v9
	v_mov_b32_e32 v17, v15
	v_pk_fma_f32 v[10:11], v[16:17], v[16:17], v[10:11]
	v_mov_b32_e32 v20, v108
	v_mov_b32_e32 v21, v109
	v_mov_b32_e32 v22, v110
	v_mov_b32_e32 v23, v111
	v_mov_b32_e32 v16, v112
	v_mov_b32_e32 v17, v113
	v_mov_b32_e32 v18, v114
	v_mov_b32_e32 v19, v115
	v_add_f32_e32 v10, v10, v11
	global_load_dwordx4 v[56:59], v[28:29], off
	v_mov_b32_e32 v42, v21
	v_mov_b32_e32 v43, v17
	v_mov_b32_e32 v4, v20
	v_mov_b32_e32 v5, v16
	v_pk_mul_f32 v[42:43], v[42:43], v[42:43]
	s_nop 0
	v_pk_fma_f32 v[4:5], v[4:5], v[4:5], v[42:43]
	v_mov_b32_e32 v42, v22
	v_mov_b32_e32 v43, v18
	v_pk_fma_f32 v[4:5], v[42:43], v[42:43], v[4:5]
	v_mov_b32_e32 v42, v23
	v_mov_b32_e32 v43, v19
	v_pk_fma_f32 v[4:5], v[42:43], v[42:43], v[4:5]
	v_lshl_add_u64 v[42:43], v[2:3], 0, s[10:11]
	v_add_f32_e32 v4, v10, v4
	v_add_f32_e32 v4, v4, v5
	ds_bpermute_b32 v5, v1, v4
	v_lshl_add_u64 v[10:11], v[42:43], 0, v[34:35]
	global_load_dwordx4 v[60:63], v[10:11], off
	s_waitcnt lgkmcnt(0)
	v_add_f32_e32 v4, v4, v5
	ds_bpermute_b32 v5, v46, v4
	s_waitcnt lgkmcnt(0)
	v_add_f32_e32 v4, v4, v5
	ds_bpermute_b32 v5, v47, v4
	s_waitcnt lgkmcnt(0)
	v_add_f32_e32 v4, v4, v5
	ds_bpermute_b32 v5, v48, v4
	s_waitcnt lgkmcnt(0)
	v_add_f32_e32 v4, v4, v5
	ds_bpermute_b32 v5, v49, v4
	s_waitcnt lgkmcnt(0)
	v_add_f32_e32 v4, v4, v5
	ds_bpermute_b32 v5, v50, v4
	s_waitcnt lgkmcnt(0)
	v_add_f32_e32 v4, v4, v5
	v_fmamk_f32 v4, v4, 0x3a800000, v234
	v_cmp_gt_f32_e64 s[74:75], s90, v4
	v_mul_f32_e32 v5, 0x4b800000, v4
	s_waitcnt vmcnt(0)
	v_add_f32_e32 v10, 1.0, v60
	v_cndmask_b32_e64 v4, v4, v5, s[74:75]
	v_rsq_f32_e32 v4, v4
	s_nop 0
	v_mul_f32_e32 v5, 0x45800000, v4
	v_cndmask_b32_e64 v54, v4, v5, s[74:75]
	global_load_dwordx4 v[2:5], v[44:45], off
	v_mul_f32_e32 v6, v6, v54
	v_mul_f32_e32 v6, v56, v6
	s_waitcnt vmcnt(0)
	v_fma_f32 v25, v10, v6, v2
	v_mul_f32_e32 v2, v7, v54
	v_mul_f32_e32 v2, v57, v2
	v_add_f32_e32 v6, 1.0, v61
	v_fma_f32 v35, v6, v2, v3
	v_mul_f32_e32 v2, v8, v54
	v_mul_f32_e32 v2, v58, v2
	v_add_f32_e32 v3, 1.0, v62
	v_fma_f32 v4, v3, v2, v4
	v_mul_f32_e32 v2, v9, v54
	v_mul_f32_e32 v2, v59, v2
	v_add_f32_e32 v3, 1.0, v63
	v_fmac_f32_e32 v5, v3, v2
	v_lshl_add_u64 v[2:3], s[80:81], 0, v[32:33]
	v_add_co_u32_e64 v2, s[74:75], s6, v2
	s_nop 1
	v_cvt_pk_bf16_f32 v6, v25, v35
	s_nop 1
	v_cvt_pk_bf16_f32 v7, v4, v5
	s_nop 1
	v_addc_co_u32_e64 v3, s[74:75], 0, v3, s[74:75]
	global_store_dwordx2 v[2:3], v[6:7], off
	v_lshl_add_u64 v[6:7], v[42:43], 0, v[36:37]
	global_load_dwordx4 v[56:59], v[28:29], off offset:1024
	global_load_dwordx4 v[8:11], v[44:45], off offset:1024
	global_load_dwordx4 v[60:63], v[6:7], off
	v_mul_f32_e32 v6, v12, v54
	s_waitcnt vmcnt(2)
	v_mul_f32_e32 v6, v56, v6
	s_waitcnt vmcnt(0)
	v_add_f32_e32 v7, 1.0, v60
	v_fma_f32 v37, v7, v6, v8
	v_mul_f32_e32 v6, v13, v54
	v_mul_f32_e32 v6, v57, v6
	v_add_f32_e32 v7, 1.0, v61
	v_fma_f32 v52, v7, v6, v9
	v_mul_f32_e32 v6, v14, v54
	v_mul_f32_e32 v6, v58, v6
	v_add_f32_e32 v7, 1.0, v62
	v_fma_f32 v53, v7, v6, v10
	v_mul_f32_e32 v6, v15, v54
	v_mul_f32_e32 v6, v59, v6
	v_add_f32_e32 v7, 1.0, v63
	v_fmac_f32_e32 v11, v7, v6
	s_nop 1
	v_cvt_pk_bf16_f32 v6, v37, v52
	s_nop 1
	v_cvt_pk_bf16_f32 v7, v53, v11
	global_store_dwordx2 v[2:3], v[6:7], off offset:512
	v_lshl_add_u64 v[56:57], v[42:43], 0, v[38:39]
	global_load_dwordx4 v[6:9], v[28:29], off offset:2048
	global_load_dwordx4 v[12:15], v[44:45], off offset:2048
	v_mul_f32_e32 v10, v20, v54
	global_load_dwordx4 v[56:59], v[56:57], off
	v_lshl_add_u64 v[42:43], v[42:43], 0, v[40:41]
	s_waitcnt vmcnt(2)
	v_mul_f32_e32 v6, v6, v10
	s_waitcnt vmcnt(0)
	v_add_f32_e32 v10, 1.0, v56
	v_fma_f32 v10, v6, v10, v12
	v_mul_f32_e32 v6, v21, v54
	v_mul_f32_e32 v6, v7, v6
	v_add_f32_e32 v7, 1.0, v57
	v_fma_f32 v12, v6, v7, v13
	v_mul_f32_e32 v6, v22, v54
	v_mul_f32_e32 v6, v8, v6
	v_add_f32_e32 v7, 1.0, v58
	v_fma_f32 v13, v6, v7, v14
	v_mul_f32_e32 v6, v23, v54
	v_mul_f32_e32 v6, v9, v6
	v_add_f32_e32 v7, 1.0, v59
	v_fmac_f32_e32 v15, v6, v7
	s_nop 1
	v_cvt_pk_bf16_f32 v6, v10, v12
	s_nop 1
	v_cvt_pk_bf16_f32 v7, v13, v15
	global_store_dwordx2 v[2:3], v[6:7], off offset:1024
	global_load_dwordx4 v[20:23], v[28:29], off offset:3072
	s_nop 0
	global_load_dwordx4 v[6:9], v[44:45], off offset:3072
	v_mul_f32_e32 v14, v16, v54
	global_load_dwordx4 v[42:45], v[42:43], off
	s_waitcnt vmcnt(2)
	v_mul_f32_e32 v14, v14, v20
	s_waitcnt vmcnt(0)
	v_add_f32_e32 v16, 1.0, v42
	v_fma_f32 v6, v14, v16, v6
	v_mul_f32_e32 v14, v17, v54
	v_mul_f32_e32 v14, v14, v21
	v_add_f32_e32 v16, 1.0, v43
	v_fma_f32 v7, v14, v16, v7
	v_mul_f32_e32 v14, v18, v54
	v_mul_f32_e32 v14, v14, v22
	v_add_f32_e32 v16, 1.0, v44
	v_fma_f32 v8, v14, v16, v8
	v_mul_f32_e32 v14, v19, v54
	v_mul_f32_e32 v14, v14, v23
	v_add_f32_e32 v16, 1.0, v45
	v_fmac_f32_e32 v9, v14, v16
	s_nop 1
	v_cvt_pk_bf16_f32 v16, v6, v7
	s_nop 1
	v_cvt_pk_bf16_f32 v17, v8, v9
	global_store_dwordx2 v[2:3], v[16:17], off offset:1536
	v_readlane_b32 s74, v254, 47
	s_nop 1
	v_add_u32_e32 v116, s74, v24
	v_min_i32_e32 v116, 0x43ff, v116
	v_mul_hi_i32 v117, v116, s100
	v_lshrrev_b32_e32 v118, 31, v117
	v_ashrrev_i32_e32 v117, 11, v117
	v_add_u32_e32 v117, v117, v118
	v_mad_i32_i24 v118, v117, s101, v116
	v_lshlrev_b32_e32 v119, 12, v118
	v_lshl_add_u32 v120, v117, 24, v119
	v_lshl_add_u32 v121, v117, 20, v119
	v_add_u32_e32 v120, 0xfff00000, v120
	v_lshrrev_b32_e32 v119, 8, v118
	v_cmp_lt_i32_e64 s[74:75], 0, v119
	v_mov_b32_e32 v122, s84
	v_mov_b32_e32 v123, s85
	v_mov_b32_e32 v118, s82
	v_mov_b32_e32 v119, s83
	v_cndmask_b32_e64 v120, v121, v120, s[74:75]
	v_mov_b32_e32 v121, 0
	v_cndmask_b32_e64 v122, v122, v118, s[74:75]
	v_cndmask_b32_e64 v123, v123, v119, s[74:75]
	v_mov_b32_e32 v118, v34
	v_mov_b32_e32 v119, 0
	v_lshl_add_u64 v[122:123], v[122:123], 0, v[120:121]
	v_lshl_add_u64 v[122:123], v[122:123], 0, v[118:119]
	global_load_dwordx4 v[100:103], v[122:123], off
	global_load_dwordx4 v[104:107], v[122:123], off offset:1024
	global_load_dwordx4 v[108:111], v[122:123], off offset:2048
	global_load_dwordx4 v[112:115], v[122:123], off offset:3072
	ds_read_b128 v[88:91], v51
	ds_read_b128 v[92:95], v51 offset:1024
	ds_read_b128 v[96:99], v51 offset:2048
	ds_read_b128 v[54:57], v51 offset:3072
	ds_read_b128 v[58:61], v51 offset:4096
	ds_read_b128 v[62:65], v51 offset:5120
	ds_read_b128 v[66:69], v51 offset:6144
	ds_read_b128 v[16:19], v51 offset:7168
	s_waitcnt lgkmcnt(7)
	v_mul_f32_e32 v2, v35, v89
	v_fmac_f32_e32 v2, v25, v88
	v_fmac_f32_e32 v2, v4, v90
	v_fmac_f32_e32 v2, v5, v91
	v_add_f32_e32 v72, 0, v2
	ds_read_b128 v[88:91], v51 offset:8192
	s_waitcnt lgkmcnt(7)
	v_mul_f32_e32 v3, v52, v93
	v_fmac_f32_e32 v3, v37, v92
	v_fmac_f32_e32 v3, v53, v94
	v_fmac_f32_e32 v3, v11, v95
	v_add_f32_e32 v72, v72, v3
	ds_read_b128 v[92:95], v51 offset:9216
	s_waitcnt lgkmcnt(7)
	v_mul_f32_e32 v3, v12, v97
	v_fmac_f32_e32 v3, v10, v96
	v_fmac_f32_e32 v3, v13, v98
	v_fmac_f32_e32 v3, v15, v99
	v_add_f32_e32 v72, v72, v3
	ds_read_b128 v[96:99], v51 offset:10240
	s_waitcnt lgkmcnt(7)
	v_mul_f32_e32 v3, v7, v55
	v_fmac_f32_e32 v3, v6, v54
	v_fmac_f32_e32 v3, v8, v56
	v_fmac_f32_e32 v3, v9, v57
	v_add_f32_e32 v72, v72, v3
	ds_read_b128 v[54:57], v51 offset:11264
	s_waitcnt lgkmcnt(7)
	v_mul_f32_e32 v2, v35, v59
	v_fmac_f32_e32 v2, v25, v58
	v_fmac_f32_e32 v2, v4, v60
	v_fmac_f32_e32 v2, v5, v61
	v_add_f32_e32 v73, 0, v2
	ds_read_b128 v[58:61], v51 offset:12288
	s_waitcnt lgkmcnt(7)
	v_mul_f32_e32 v3, v52, v63
	v_fmac_f32_e32 v3, v37, v62
	v_fmac_f32_e32 v3, v53, v64
	v_fmac_f32_e32 v3, v11, v65
	v_add_f32_e32 v73, v73, v3
	ds_read_b128 v[62:65], v51 offset:13312
	s_waitcnt lgkmcnt(7)
	v_mul_f32_e32 v3, v12, v67
	v_fmac_f32_e32 v3, v10, v66
	v_fmac_f32_e32 v3, v13, v68
	v_fmac_f32_e32 v3, v15, v69
	v_add_f32_e32 v73, v73, v3
	ds_read_b128 v[66:69], v51 offset:14336
	s_waitcnt lgkmcnt(7)
	v_mul_f32_e32 v3, v7, v17
	v_fmac_f32_e32 v3, v6, v16
	v_fmac_f32_e32 v3, v8, v18
	v_fmac_f32_e32 v3, v9, v19
	v_add_f32_e32 v73, v73, v3
	ds_read_b128 v[16:19], v51 offset:15360
	s_waitcnt lgkmcnt(7)
	v_mul_f32_e32 v2, v35, v89
	v_fmac_f32_e32 v2, v25, v88
	v_fmac_f32_e32 v2, v4, v90
	v_fmac_f32_e32 v2, v5, v91
	v_add_f32_e32 v74, 0, v2
	ds_read_b128 v[88:91], v51 offset:16384
	s_waitcnt lgkmcnt(7)
	v_mul_f32_e32 v3, v52, v93
	v_fmac_f32_e32 v3, v37, v92
	v_fmac_f32_e32 v3, v53, v94
	v_fmac_f32_e32 v3, v11, v95
	v_add_f32_e32 v74, v74, v3
	ds_read_b128 v[92:95], v51 offset:17408
	s_waitcnt lgkmcnt(7)
	v_mul_f32_e32 v3, v12, v97
	v_fmac_f32_e32 v3, v10, v96
	v_fmac_f32_e32 v3, v13, v98
	v_fmac_f32_e32 v3, v15, v99
	v_add_f32_e32 v74, v74, v3
	ds_read_b128 v[96:99], v51 offset:18432
	s_waitcnt lgkmcnt(7)
	v_mul_f32_e32 v3, v7, v55
	v_fmac_f32_e32 v3, v6, v54
	v_fmac_f32_e32 v3, v8, v56
	v_fmac_f32_e32 v3, v9, v57
	v_add_f32_e32 v74, v74, v3
	ds_read_b128 v[54:57], v51 offset:19456
	s_waitcnt lgkmcnt(7)
	v_mul_f32_e32 v2, v35, v59
	v_fmac_f32_e32 v2, v25, v58
	v_fmac_f32_e32 v2, v4, v60
	v_fmac_f32_e32 v2, v5, v61
	v_add_f32_e32 v75, 0, v2
	ds_read_b128 v[58:61], v51 offset:20480
	s_waitcnt lgkmcnt(7)
	v_mul_f32_e32 v3, v52, v63
	v_fmac_f32_e32 v3, v37, v62
	v_fmac_f32_e32 v3, v53, v64
	v_fmac_f32_e32 v3, v11, v65
	v_add_f32_e32 v75, v75, v3
	ds_read_b128 v[62:65], v51 offset:21504
	s_waitcnt lgkmcnt(7)
	v_mul_f32_e32 v3, v12, v67
	v_fmac_f32_e32 v3, v10, v66
	v_fmac_f32_e32 v3, v13, v68
	v_fmac_f32_e32 v3, v15, v69
	v_add_f32_e32 v75, v75, v3
	ds_read_b128 v[66:69], v51 offset:22528
	s_waitcnt lgkmcnt(7)
	v_mul_f32_e32 v3, v7, v17
	v_fmac_f32_e32 v3, v6, v16
	v_fmac_f32_e32 v3, v8, v18
	v_fmac_f32_e32 v3, v9, v19
	v_add_f32_e32 v75, v75, v3
	ds_read_b128 v[16:19], v51 offset:23552
	s_waitcnt lgkmcnt(7)
	v_mul_f32_e32 v2, v35, v89
	v_fmac_f32_e32 v2, v25, v88
	v_fmac_f32_e32 v2, v4, v90
	v_fmac_f32_e32 v2, v5, v91
	v_add_f32_e32 v76, 0, v2
	ds_read_b128 v[88:91], v51 offset:24576
	s_waitcnt lgkmcnt(7)
	v_mul_f32_e32 v3, v52, v93
	v_fmac_f32_e32 v3, v37, v92
	v_fmac_f32_e32 v3, v53, v94
	v_fmac_f32_e32 v3, v11, v95
	v_add_f32_e32 v76, v76, v3
	ds_read_b128 v[92:95], v51 offset:25600
	s_waitcnt lgkmcnt(7)
	v_mul_f32_e32 v3, v12, v97
	v_fmac_f32_e32 v3, v10, v96
	v_fmac_f32_e32 v3, v13, v98
	v_fmac_f32_e32 v3, v15, v99
	v_add_f32_e32 v76, v76, v3
	ds_read_b128 v[96:99], v51 offset:26624
	s_waitcnt lgkmcnt(7)
	v_mul_f32_e32 v3, v7, v55
	v_fmac_f32_e32 v3, v6, v54
	v_fmac_f32_e32 v3, v8, v56
	v_fmac_f32_e32 v3, v9, v57
	v_add_f32_e32 v76, v76, v3
	ds_read_b128 v[54:57], v51 offset:27648
	s_waitcnt lgkmcnt(7)
	v_mul_f32_e32 v2, v35, v59
	v_fmac_f32_e32 v2, v25, v58
	v_fmac_f32_e32 v2, v4, v60
	v_fmac_f32_e32 v2, v5, v61
	v_add_f32_e32 v77, 0, v2
	ds_read_b128 v[58:61], v51 offset:28672
	s_waitcnt lgkmcnt(7)
	v_mul_f32_e32 v3, v52, v63
	v_fmac_f32_e32 v3, v37, v62
	v_fmac_f32_e32 v3, v53, v64
	v_fmac_f32_e32 v3, v11, v65
	v_add_f32_e32 v77, v77, v3
	ds_read_b128 v[62:65], v51 offset:29696
	s_waitcnt lgkmcnt(7)
	v_mul_f32_e32 v3, v12, v67
	v_fmac_f32_e32 v3, v10, v66
	v_fmac_f32_e32 v3, v13, v68
	v_fmac_f32_e32 v3, v15, v69
	v_add_f32_e32 v77, v77, v3
	ds_read_b128 v[66:69], v51 offset:30720
	s_waitcnt lgkmcnt(7)
	v_mul_f32_e32 v3, v7, v17
	v_fmac_f32_e32 v3, v6, v16
	v_fmac_f32_e32 v3, v8, v18
	v_fmac_f32_e32 v3, v9, v19
	v_add_f32_e32 v77, v77, v3
	ds_read_b128 v[16:19], v51 offset:31744
	s_waitcnt lgkmcnt(7)
	v_mul_f32_e32 v2, v35, v89
	v_fmac_f32_e32 v2, v25, v88
	v_fmac_f32_e32 v2, v4, v90
	v_fmac_f32_e32 v2, v5, v91
	v_add_f32_e32 v78, 0, v2
	ds_read_b128 v[88:91], v51 offset:32768
	s_waitcnt lgkmcnt(7)
	v_mul_f32_e32 v3, v52, v93
	v_fmac_f32_e32 v3, v37, v92
	v_fmac_f32_e32 v3, v53, v94
	v_fmac_f32_e32 v3, v11, v95
	v_add_f32_e32 v78, v78, v3
	ds_read_b128 v[92:95], v51 offset:33792
	s_waitcnt lgkmcnt(7)
	v_mul_f32_e32 v3, v12, v97
	v_fmac_f32_e32 v3, v10, v96
	v_fmac_f32_e32 v3, v13, v98
	v_fmac_f32_e32 v3, v15, v99
	v_add_f32_e32 v78, v78, v3
	ds_read_b128 v[96:99], v51 offset:34816
	s_waitcnt lgkmcnt(7)
	v_mul_f32_e32 v3, v7, v55
	v_fmac_f32_e32 v3, v6, v54
	v_fmac_f32_e32 v3, v8, v56
	v_fmac_f32_e32 v3, v9, v57
	v_add_f32_e32 v78, v78, v3
	ds_read_b128 v[54:57], v51 offset:35840
	s_waitcnt lgkmcnt(7)
	v_mul_f32_e32 v2, v35, v59
	v_fmac_f32_e32 v2, v25, v58
	v_fmac_f32_e32 v2, v4, v60
	v_fmac_f32_e32 v2, v5, v61
	v_add_f32_e32 v79, 0, v2
	ds_read_b128 v[58:61], v51 offset:36864
	s_waitcnt lgkmcnt(7)
	v_mul_f32_e32 v3, v52, v63
	v_fmac_f32_e32 v3, v37, v62
	v_fmac_f32_e32 v3, v53, v64
	v_fmac_f32_e32 v3, v11, v65
	v_add_f32_e32 v79, v79, v3
	ds_read_b128 v[62:65], v51 offset:37888
	s_waitcnt lgkmcnt(7)
	v_mul_f32_e32 v3, v12, v67
	v_fmac_f32_e32 v3, v10, v66
	v_fmac_f32_e32 v3, v13, v68
	v_fmac_f32_e32 v3, v15, v69
	v_add_f32_e32 v79, v79, v3
	ds_read_b128 v[66:69], v51 offset:38912
	s_waitcnt lgkmcnt(7)
	v_mul_f32_e32 v3, v7, v17
	v_fmac_f32_e32 v3, v6, v16
	v_fmac_f32_e32 v3, v8, v18
	v_fmac_f32_e32 v3, v9, v19
	v_add_f32_e32 v79, v79, v3
	ds_read_b128 v[16:19], v51 offset:39936
	s_waitcnt lgkmcnt(7)
	v_mul_f32_e32 v2, v35, v89
	v_fmac_f32_e32 v2, v25, v88
	v_fmac_f32_e32 v2, v4, v90
	v_fmac_f32_e32 v2, v5, v91
	v_add_f32_e32 v80, 0, v2
	ds_read_b128 v[88:91], v51 offset:40960
	s_waitcnt lgkmcnt(7)
	v_mul_f32_e32 v3, v52, v93
	v_fmac_f32_e32 v3, v37, v92
	v_fmac_f32_e32 v3, v53, v94
	v_fmac_f32_e32 v3, v11, v95
	v_add_f32_e32 v80, v80, v3
	ds_read_b128 v[92:95], v51 offset:41984
	s_waitcnt lgkmcnt(7)
	v_mul_f32_e32 v3, v12, v97
	v_fmac_f32_e32 v3, v10, v96
	v_fmac_f32_e32 v3, v13, v98
	v_fmac_f32_e32 v3, v15, v99
	v_add_f32_e32 v80, v80, v3
	ds_read_b128 v[96:99], v51 offset:43008
	s_waitcnt lgkmcnt(7)
	v_mul_f32_e32 v3, v7, v55
	v_fmac_f32_e32 v3, v6, v54
	v_fmac_f32_e32 v3, v8, v56
	v_fmac_f32_e32 v3, v9, v57
	v_add_f32_e32 v80, v80, v3
	ds_read_b128 v[54:57], v51 offset:44032
	s_waitcnt lgkmcnt(7)
	v_mul_f32_e32 v2, v35, v59
	v_fmac_f32_e32 v2, v25, v58
	v_fmac_f32_e32 v2, v4, v60
	v_fmac_f32_e32 v2, v5, v61
	v_add_f32_e32 v81, 0, v2
	ds_read_b128 v[58:61], v51 offset:45056
	s_waitcnt lgkmcnt(7)
	v_mul_f32_e32 v3, v52, v63
	v_fmac_f32_e32 v3, v37, v62
	v_fmac_f32_e32 v3, v53, v64
	v_fmac_f32_e32 v3, v11, v65
	v_add_f32_e32 v81, v81, v3
	ds_read_b128 v[62:65], v51 offset:46080
	s_waitcnt lgkmcnt(7)
	v_mul_f32_e32 v3, v12, v67
	v_fmac_f32_e32 v3, v10, v66
	v_fmac_f32_e32 v3, v13, v68
	v_fmac_f32_e32 v3, v15, v69
	v_add_f32_e32 v81, v81, v3
	ds_read_b128 v[66:69], v51 offset:47104
	s_waitcnt lgkmcnt(7)
	v_mul_f32_e32 v3, v7, v17
	v_fmac_f32_e32 v3, v6, v16
	v_fmac_f32_e32 v3, v8, v18
	v_fmac_f32_e32 v3, v9, v19
	v_add_f32_e32 v81, v81, v3
	ds_read_b128 v[16:19], v51 offset:48128
	s_waitcnt lgkmcnt(7)
	v_mul_f32_e32 v2, v35, v89
	v_fmac_f32_e32 v2, v25, v88
	v_fmac_f32_e32 v2, v4, v90
	v_fmac_f32_e32 v2, v5, v91
	v_add_f32_e32 v82, 0, v2
	ds_read_b128 v[88:91], v51 offset:49152
	s_waitcnt lgkmcnt(7)
	v_mul_f32_e32 v3, v52, v93
	v_fmac_f32_e32 v3, v37, v92
	v_fmac_f32_e32 v3, v53, v94
	v_fmac_f32_e32 v3, v11, v95
	v_add_f32_e32 v82, v82, v3
	ds_read_b128 v[92:95], v51 offset:50176
	s_waitcnt lgkmcnt(7)
	v_mul_f32_e32 v3, v12, v97
	v_fmac_f32_e32 v3, v10, v96
	v_fmac_f32_e32 v3, v13, v98
	v_fmac_f32_e32 v3, v15, v99
	v_add_f32_e32 v82, v82, v3
	ds_read_b128 v[96:99], v51 offset:51200
	s_waitcnt lgkmcnt(7)
	v_mul_f32_e32 v3, v7, v55
	v_fmac_f32_e32 v3, v6, v54
	v_fmac_f32_e32 v3, v8, v56
	v_fmac_f32_e32 v3, v9, v57
	v_add_f32_e32 v82, v82, v3
	ds_read_b128 v[54:57], v51 offset:52224
	s_waitcnt lgkmcnt(7)
	v_mul_f32_e32 v2, v35, v59
	v_fmac_f32_e32 v2, v25, v58
	v_fmac_f32_e32 v2, v4, v60
	v_fmac_f32_e32 v2, v5, v61
	v_add_f32_e32 v83, 0, v2
	ds_read_b128 v[58:61], v51 offset:53248
	s_waitcnt lgkmcnt(7)
	v_mul_f32_e32 v3, v52, v63
	v_fmac_f32_e32 v3, v37, v62
	v_fmac_f32_e32 v3, v53, v64
	v_fmac_f32_e32 v3, v11, v65
	v_add_f32_e32 v83, v83, v3
	ds_read_b128 v[62:65], v51 offset:54272
	s_waitcnt lgkmcnt(7)
	v_mul_f32_e32 v3, v12, v67
	v_fmac_f32_e32 v3, v10, v66
	v_fmac_f32_e32 v3, v13, v68
	v_fmac_f32_e32 v3, v15, v69
	v_add_f32_e32 v83, v83, v3
	ds_read_b128 v[66:69], v51 offset:55296
	s_waitcnt lgkmcnt(7)
	v_mul_f32_e32 v3, v7, v17
	v_fmac_f32_e32 v3, v6, v16
	v_fmac_f32_e32 v3, v8, v18
	v_fmac_f32_e32 v3, v9, v19
	v_add_f32_e32 v83, v83, v3
	ds_read_b128 v[16:19], v51 offset:56320
	s_waitcnt lgkmcnt(7)
	v_mul_f32_e32 v2, v35, v89
	v_fmac_f32_e32 v2, v25, v88
	v_fmac_f32_e32 v2, v4, v90
	v_fmac_f32_e32 v2, v5, v91
	v_add_f32_e32 v84, 0, v2
	ds_read_b128 v[88:91], v51 offset:57344
	s_waitcnt lgkmcnt(7)
	v_mul_f32_e32 v3, v52, v93
	v_fmac_f32_e32 v3, v37, v92
	v_fmac_f32_e32 v3, v53, v94
	v_fmac_f32_e32 v3, v11, v95
	v_add_f32_e32 v84, v84, v3
	ds_read_b128 v[92:95], v51 offset:58368
	s_waitcnt lgkmcnt(7)
	v_mul_f32_e32 v3, v12, v97
	v_fmac_f32_e32 v3, v10, v96
	v_fmac_f32_e32 v3, v13, v98
	v_fmac_f32_e32 v3, v15, v99
	v_add_f32_e32 v84, v84, v3
	ds_read_b128 v[96:99], v51 offset:59392
	s_waitcnt lgkmcnt(7)
	v_mul_f32_e32 v3, v7, v55
	v_fmac_f32_e32 v3, v6, v54
	v_fmac_f32_e32 v3, v8, v56
	v_fmac_f32_e32 v3, v9, v57
	v_add_f32_e32 v84, v84, v3
	ds_read_b128 v[54:57], v51 offset:60416
	s_waitcnt lgkmcnt(7)
	v_mul_f32_e32 v2, v35, v59
	v_fmac_f32_e32 v2, v25, v58
	v_fmac_f32_e32 v2, v4, v60
	v_fmac_f32_e32 v2, v5, v61
	v_add_f32_e32 v85, 0, v2
	ds_read_b128 v[58:61], v51 offset:61440
	s_waitcnt lgkmcnt(7)
	v_mul_f32_e32 v3, v52, v63
	v_fmac_f32_e32 v3, v37, v62
	v_fmac_f32_e32 v3, v53, v64
	v_fmac_f32_e32 v3, v11, v65
	v_add_f32_e32 v85, v85, v3
	ds_read_b128 v[62:65], v51 offset:62464
	s_waitcnt lgkmcnt(7)
	v_mul_f32_e32 v3, v12, v67
	v_fmac_f32_e32 v3, v10, v66
	v_fmac_f32_e32 v3, v13, v68
	v_fmac_f32_e32 v3, v15, v69
	v_add_f32_e32 v85, v85, v3
	ds_read_b128 v[66:69], v51 offset:63488
	s_waitcnt lgkmcnt(7)
	v_mul_f32_e32 v3, v7, v17
	v_fmac_f32_e32 v3, v6, v16
	v_fmac_f32_e32 v3, v8, v18
	v_fmac_f32_e32 v3, v9, v19
	v_add_f32_e32 v85, v85, v3
	ds_read_b128 v[16:19], v51 offset:64512
	s_waitcnt lgkmcnt(7)
	v_mul_f32_e32 v2, v35, v89
	v_fmac_f32_e32 v2, v25, v88
	v_fmac_f32_e32 v2, v4, v90
	v_fmac_f32_e32 v2, v5, v91
	v_add_f32_e32 v86, 0, v2
	s_waitcnt lgkmcnt(6)
	v_mul_f32_e32 v3, v52, v93
	v_fmac_f32_e32 v3, v37, v92
	v_fmac_f32_e32 v3, v53, v94
	v_fmac_f32_e32 v3, v11, v95
	v_add_f32_e32 v86, v86, v3
	s_waitcnt lgkmcnt(5)
	v_mul_f32_e32 v3, v12, v97
	v_fmac_f32_e32 v3, v10, v96
	v_fmac_f32_e32 v3, v13, v98
	v_fmac_f32_e32 v3, v15, v99
	v_add_f32_e32 v86, v86, v3
	s_waitcnt lgkmcnt(4)
	v_mul_f32_e32 v3, v7, v55
	v_fmac_f32_e32 v3, v6, v54
	v_fmac_f32_e32 v3, v8, v56
	v_fmac_f32_e32 v3, v9, v57
	v_add_f32_e32 v86, v86, v3
	s_waitcnt lgkmcnt(3)
	v_mul_f32_e32 v2, v35, v59
	v_fmac_f32_e32 v2, v25, v58
	v_fmac_f32_e32 v2, v4, v60
	v_fmac_f32_e32 v2, v5, v61
	v_add_f32_e32 v87, 0, v2
	s_waitcnt lgkmcnt(2)
	v_mul_f32_e32 v3, v52, v63
	v_fmac_f32_e32 v3, v37, v62
	v_fmac_f32_e32 v3, v53, v64
	v_fmac_f32_e32 v3, v11, v65
	v_add_f32_e32 v87, v87, v3
	s_waitcnt lgkmcnt(1)
	v_mul_f32_e32 v3, v12, v67
	v_fmac_f32_e32 v3, v10, v66
	v_fmac_f32_e32 v3, v13, v68
	v_fmac_f32_e32 v3, v15, v69
	v_add_f32_e32 v87, v87, v3
	s_waitcnt lgkmcnt(0)
	v_mul_f32_e32 v3, v7, v17
	v_fmac_f32_e32 v3, v6, v16
	v_fmac_f32_e32 v3, v8, v18
	v_fmac_f32_e32 v3, v9, v19
	v_add_f32_e32 v87, v87, v3
	s_mov_b32 s42, 0xcccccccc
	s_mov_b32 s43, 0xcccccccc
	s_mov_b32 s44, 0xaaaaaaaa
	s_mov_b32 s45, 0xaaaaaaaa
	s_nop 1
	v_add_f32_dpp v16, v72, v72 row_shl:8 row_mask:0xf bank_mask:0x3
	v_add_f32_dpp v16, v80, v80 row_shr:8 row_mask:0xf bank_mask:0xc
	v_add_f32_dpp v17, v73, v73 row_shl:8 row_mask:0xf bank_mask:0x3
	v_add_f32_dpp v17, v81, v81 row_shr:8 row_mask:0xf bank_mask:0xc
	v_add_f32_dpp v18, v74, v74 row_shl:8 row_mask:0xf bank_mask:0x3
	v_add_f32_dpp v18, v82, v82 row_shr:8 row_mask:0xf bank_mask:0xc
	v_add_f32_dpp v19, v75, v75 row_shl:8 row_mask:0xf bank_mask:0x3
	v_add_f32_dpp v19, v83, v83 row_shr:8 row_mask:0xf bank_mask:0xc
	v_add_f32_dpp v20, v76, v76 row_shl:8 row_mask:0xf bank_mask:0x3
	v_add_f32_dpp v20, v84, v84 row_shr:8 row_mask:0xf bank_mask:0xc
	v_add_f32_dpp v21, v77, v77 row_shl:8 row_mask:0xf bank_mask:0x3
	v_add_f32_dpp v21, v85, v85 row_shr:8 row_mask:0xf bank_mask:0xc
	v_add_f32_dpp v22, v78, v78 row_shl:8 row_mask:0xf bank_mask:0x3
	v_add_f32_dpp v22, v86, v86 row_shr:8 row_mask:0xf bank_mask:0xc
	v_add_f32_dpp v23, v79, v79 row_shl:8 row_mask:0xf bank_mask:0x3
	v_add_f32_dpp v23, v87, v87 row_shr:8 row_mask:0xf bank_mask:0xc
	s_nop 1
	v_add_f32_dpp v39, v16, v16 row_shl:4 row_mask:0xf bank_mask:0x5
	v_add_f32_dpp v39, v20, v20 row_shr:4 row_mask:0xf bank_mask:0xa
	v_add_f32_dpp v41, v17, v17 row_shl:4 row_mask:0xf bank_mask:0x5
	v_add_f32_dpp v41, v21, v21 row_shr:4 row_mask:0xf bank_mask:0xa
	v_add_f32_dpp v42, v18, v18 row_shl:4 row_mask:0xf bank_mask:0x5
	v_add_f32_dpp v42, v22, v22 row_shr:4 row_mask:0xf bank_mask:0xa
	v_add_f32_dpp v43, v19, v19 row_shl:4 row_mask:0xf bank_mask:0x5
	v_add_f32_dpp v43, v23, v23 row_shr:4 row_mask:0xf bank_mask:0xa
	v_cndmask_b32_e64 v14, v39, v42, s[42:43]
	v_cndmask_b32_e64 v3, v42, v39, s[42:43]
	v_cndmask_b32_e64 v54, v41, v43, s[42:43]
	v_cndmask_b32_e64 v55, v43, v41, s[42:43]
	s_nop 1
	v_add_f32_dpp v44, v3, v14 quad_perm:[2,3,0,1] row_mask:0xf bank_mask:0xf
	v_add_f32_dpp v45, v55, v54 quad_perm:[2,3,0,1] row_mask:0xf bank_mask:0xf
	v_cndmask_b32_e64 v14, v44, v45, s[44:45]
	v_cndmask_b32_e64 v3, v45, v44, s[44:45]
	s_nop 1
	v_add_f32_dpp v2, v3, v14 quad_perm:[1,0,3,2] row_mask:0xf bank_mask:0xf
	v_mov_b32_e32 v3, v2
	s_nop 1
	v_permlane16_swap_b32_e32 v3, v2
	s_nop 1
	v_add_f32_e32 v2, v3, v2
	v_mov_b32_e32 v3, v2
	s_nop 1
	v_permlane32_swap_b32_e32 v3, v2
	s_nop 1
	v_add_f32_e32 v2, v3, v2
	s_and_saveexec_b64 s[10:11], vcc
	s_cbranch_execz .LBB0_170
	s_load_dwordx2 s[14:15], s[12:13], 0x40
	s_waitcnt lgkmcnt(0)
	v_lshl_add_u64 v[6:7], v[26:27], 2, s[14:15]
	global_load_dword v6, v[6:7], off
	s_waitcnt vmcnt(0)
	v_add_f32_e32 v2, v2, v6
	s_and_saveexec_b64 s[14:15], s[40:41]
	s_cbranch_execz .LBB0_169
	s_mov_b32 s6, 0xbfb8aa3b
	v_mul_f32_e64 v3, |v2|, s6
	v_exp_f32_e32 v3, v3
	s_mov_b32 s6, 0x3f317217
	v_max_f32_e32 v2, v2, v2
	v_min_f32_e32 v2, 0, v2
	v_add_f32_e32 v3, 1.0, v3
	v_cmp_gt_f32_e64 s[74:75], s90, v3
	s_nop 1
	v_cndmask_b32_e64 v4, 0, 32, s[74:75]
	v_ldexp_f32 v3, v3, v4
	v_log_f32_e32 v3, v3
	s_nop 0
	v_mul_f32_e32 v4, 0x3f317217, v3
	v_fma_f32 v4, v3, s6, -v4
	v_fmac_f32_e32 v4, 0x3377d1cf, v3
	s_mov_b32 s6, 0x7f800000
	v_fmac_f32_e32 v4, 0x3f317217, v3
	v_cmp_lt_f32_e64 s[76:77], |v3|, s6
	s_nop 1
	v_cndmask_b32_e64 v3, v3, v4, s[76:77]
	v_mov_b32_e32 v4, 0x41b17218
	v_cndmask_b32_e64 v4, 0, v4, s[74:75]
	v_sub_f32_e32 v3, v3, v4
	v_sub_f32_e32 v2, v2, v3
	s_branch .LBB0_169

.LBB0_388:
	v_ashrrev_i32_e32 v35, 31, v34
	v_lshlrev_b64 v[40:41], 11, v[34:35]
	v_lshl_add_u64 v[42:43], v[36:37], 0, v[40:41]
	s_waitcnt vmcnt(6)
	v_mov_b32_e32 v44, v100
	v_mov_b32_e32 v45, v101
	v_mov_b32_e32 v46, v102
	v_mov_b32_e32 v47, v103
	v_mov_b32_e32 v48, v104
	v_mov_b32_e32 v49, v105
	v_mov_b32_e32 v50, v106
	v_mov_b32_e32 v51, v107
	v_lshl_add_u64 v[96:97], s[100:101], 0, v[42:43]
	global_load_dwordx4 v[100:103], v[96:97], off offset:16
	global_load_dwordx4 v[104:107], v[96:97], off
	s_mov_b32 s6, 0x78787879
	v_mul_hi_i32 v35, v34, s6
	s_movk_i32 s6, 0xff
	v_lshlrev_b32_e32 v58, 16, v44
	v_lshlrev_b32_e32 v54, 16, v48
	v_and_b32_e32 v55, 0xffff0000, v48
	v_lshlrev_b32_e32 v48, 16, v49
	v_and_b32_e32 v49, 0xffff0000, v49
	v_pk_mul_f32 v[64:65], v[54:55], v[54:55]
	v_pk_mul_f32 v[66:67], v[48:49], v[48:49]
	v_add_f32_e32 v61, v64, v65
	v_lshlrev_b32_e32 v56, 16, v50
	v_and_b32_e32 v57, 0xffff0000, v50
	v_add_f32_e32 v61, v66, v61
	v_pk_mul_f32 v[68:69], v[56:57], v[56:57]
	v_add_f32_e32 v61, v67, v61
	v_lshlrev_b32_e32 v50, 16, v51
	v_and_b32_e32 v51, 0xffff0000, v51
	v_add_f32_e32 v61, v68, v61
	v_pk_mul_f32 v[70:71], v[50:51], v[50:51]
	v_add_f32_e32 v61, v69, v61
	v_and_b32_e32 v59, 0xffff0000, v44
	v_add_f32_e32 v61, v70, v61
	v_pk_mul_f32 v[72:73], v[58:59], v[58:59]
	v_add_f32_e32 v61, v71, v61
	v_lshlrev_b32_e32 v44, 16, v45
	v_and_b32_e32 v45, 0xffff0000, v45
	v_add_f32_e32 v61, v72, v61
	v_pk_mul_f32 v[74:75], v[44:45], v[44:45]
	v_add_f32_e32 v61, v73, v61
	v_lshlrev_b32_e32 v62, 16, v46
	v_and_b32_e32 v63, 0xffff0000, v46
	v_add_f32_e32 v61, v74, v61
	v_pk_mul_f32 v[76:77], v[62:63], v[62:63]
	v_add_f32_e32 v61, v75, v61
	v_and_b32_e32 v52, 0xffff0000, v47
	v_lshlrev_b32_e32 v53, 16, v47
	v_add_f32_e32 v61, v76, v61
	v_pk_mul_f32 v[46:47], v[52:53], v[52:53]
	v_add_f32_e32 v61, v77, v61
	v_add_f32_e32 v47, v47, v61
	v_add_f32_e32 v46, v46, v47
	s_nop 1
	v_mov_b32_dpp v47, v46 quad_perm:[1,0,3,2] row_mask:0xf bank_mask:0xf
	v_lshrrev_b32_e32 v61, 31, v35
	v_ashrrev_i32_e32 v35, 11, v35
	v_add_u32_e32 v35, v35, v61
	v_mul_i32_i24_e32 v35, 0x1100, v35
	v_add_f32_e32 v46, v46, v47
	s_nop 1
	v_mov_b32_dpp v47, v46 quad_perm:[2,3,0,1] row_mask:0xf bank_mask:0xf
	v_sub_u32_e32 v35, v34, v35
	v_add_u32_e32 v61, 0xffffff00, v35
	v_cmp_lt_i32_e64 s[42:43], s6, v35
	v_and_b32_e32 v35, 63, v35
	v_add_f32_e32 v46, v46, v47
	v_fmamk_f32 v46, v46, 0x3c800000, v234
	v_mul_f32_e32 v47, 0x4b800000, v46
	v_cmp_gt_f32_e64 s[44:45], s90, v46
	s_nop 1
	v_cndmask_b32_e64 v46, v46, v47, s[44:45]
	v_rsq_f32_e32 v46, v46
	v_ashrrev_i32_e32 v47, 6, v61
	v_cndmask_b32_e32 v35, v35, v47, vcc
	v_lshlrev_b32_e32 v35, 4, v35
	v_mul_f32_e32 v47, 0x45800000, v46
	v_cndmask_b32_e64 v46, v46, v47, s[44:45]
	v_pk_mul_f32 v[54:55], v[46:47], v[54:55] op_sel_hi:[0,1]
	v_pk_mul_f32 v[48:49], v[46:47], v[48:49] op_sel_hi:[0,1]
	v_pk_mul_f32 v[64:65], v[46:47], v[56:57] op_sel_hi:[0,1]
	v_pk_mul_f32 v[50:51], v[46:47], v[50:51] op_sel_hi:[0,1]
	v_pk_mul_f32 v[66:67], v[46:47], v[58:59] op_sel_hi:[0,1]
	v_pk_mul_f32 v[44:45], v[46:47], v[44:45] op_sel_hi:[0,1]
	v_pk_mul_f32 v[62:63], v[46:47], v[62:63] op_sel_hi:[0,1]
	v_pk_mul_f32 v[68:69], v[46:47], v[52:53] op_sel_hi:[0,1]
	v_pk_mul_f32 v[58:59], v[30:31], v[54:55]
	v_pk_mul_f32 v[56:57], v[32:33], v[48:49]
	v_pk_mul_f32 v[54:55], v[26:27], v[64:65]
	v_pk_mul_f32 v[52:53], v[28:29], v[50:51]
	v_pk_mul_f32 v[50:51], v[22:23], v[66:67]
	v_pk_mul_f32 v[48:49], v[24:25], v[44:45]
	v_pk_mul_f32 v[46:47], v[18:19], v[62:63]
	v_pk_mul_f32 v[44:45], v[20:21], v[68:69] op_sel:[0,1] op_sel_hi:[1,0]
	v_lshl_add_u32 v35, v35, 2, 0
	s_and_saveexec_b64 s[14:15], s[42:43]
	s_cbranch_execz .LBB0_390
	v_mov_b32_dpp v82, v58 quad_perm:[1,0,3,2] row_mask:0xf bank_mask:0xf
	v_mov_b32_dpp v83, v59 quad_perm:[1,0,3,2] row_mask:0xf bank_mask:0xf
	ds_read_b128 v[62:65], v35
	ds_read_b128 v[66:69], v35 offset:16
	ds_read_b128 v[70:73], v35 offset:32
	ds_read_b128 v[74:77], v35 offset:48
	ds_read_b128 v[78:81], v35 offset:4096
	v_mov_b32_dpp v86, v54 quad_perm:[1,0,3,2] row_mask:0xf bank_mask:0xf
	v_mov_b32_dpp v87, v55 quad_perm:[1,0,3,2] row_mask:0xf bank_mask:0xf
	v_mov_b32_dpp v90, v50 quad_perm:[1,0,3,2] row_mask:0xf bank_mask:0xf
	v_mov_b32_dpp v91, v51 quad_perm:[1,0,3,2] row_mask:0xf bank_mask:0xf
	s_waitcnt lgkmcnt(0)
	v_pk_mul_f32 v[82:83], v[78:79], v[82:83]
	v_mov_b32_dpp v78, v56 quad_perm:[1,0,3,2] row_mask:0xf bank_mask:0xf
	v_mov_b32_dpp v79, v57 quad_perm:[1,0,3,2] row_mask:0xf bank_mask:0xf
	v_mov_b32_dpp v94, v46 quad_perm:[1,0,3,2] row_mask:0xf bank_mask:0xf
	v_mov_b32_dpp v95, v47 quad_perm:[1,0,3,2] row_mask:0xf bank_mask:0xf
	v_cndmask_b32_e64 v83, v83, -v83, s[40:41]
	v_cndmask_b32_e64 v82, v82, -v82, s[40:41]
	v_pk_mul_f32 v[84:85], v[80:81], v[78:79]
	ds_read_b128 v[78:81], v35 offset:4112
	v_cndmask_b32_e64 v85, v85, -v85, s[40:41]
	v_cndmask_b32_e64 v84, v84, -v84, s[40:41]
	v_pk_fma_f32 v[56:57], v[56:57], v[64:65], v[84:85]
	v_pk_fma_f32 v[58:59], v[58:59], v[62:63], v[82:83]
	s_waitcnt lgkmcnt(0)
	v_pk_mul_f32 v[86:87], v[78:79], v[86:87]
	v_mov_b32_dpp v78, v52 quad_perm:[1,0,3,2] row_mask:0xf bank_mask:0xf
	v_mov_b32_dpp v79, v53 quad_perm:[1,0,3,2] row_mask:0xf bank_mask:0xf
	v_cndmask_b32_e64 v87, v87, -v87, s[40:41]
	v_cndmask_b32_e64 v86, v86, -v86, s[40:41]
	v_pk_fma_f32 v[54:55], v[54:55], v[66:67], v[86:87]
	v_pk_mul_f32 v[88:89], v[80:81], v[78:79]
	ds_read_b128 v[78:81], v35 offset:4128
	v_cndmask_b32_e64 v88, v88, -v88, s[40:41]
	v_cndmask_b32_e64 v89, v89, -v89, s[40:41]
	v_pk_fma_f32 v[52:53], v[52:53], v[68:69], v[88:89]
	s_waitcnt lgkmcnt(0)
	v_pk_mul_f32 v[90:91], v[78:79], v[90:91]
	v_mov_b32_dpp v78, v48 quad_perm:[1,0,3,2] row_mask:0xf bank_mask:0xf
	v_mov_b32_dpp v79, v49 quad_perm:[1,0,3,2] row_mask:0xf bank_mask:0xf
	v_cndmask_b32_e64 v90, v90, -v90, s[40:41]
	v_cndmask_b32_e64 v91, v91, -v91, s[40:41]
	v_pk_fma_f32 v[50:51], v[50:51], v[70:71], v[90:91]
	v_pk_mul_f32 v[92:93], v[80:81], v[78:79]
	ds_read_b128 v[78:81], v35 offset:4144
	v_cndmask_b32_e64 v92, v92, -v92, s[40:41]
	v_cndmask_b32_e64 v93, v93, -v93, s[40:41]
	v_pk_fma_f32 v[48:49], v[48:49], v[72:73], v[92:93]
	s_waitcnt lgkmcnt(0)
	v_pk_mul_f32 v[78:79], v[78:79], v[94:95]
	v_mov_b32_dpp v94, v44 quad_perm:[1,0,3,2] row_mask:0xf bank_mask:0xf
	v_mov_b32_dpp v95, v45 quad_perm:[1,0,3,2] row_mask:0xf bank_mask:0xf
	v_cndmask_b32_e64 v78, v78, -v78, s[40:41]
	v_cndmask_b32_e64 v79, v79, -v79, s[40:41]
	v_pk_fma_f32 v[46:47], v[46:47], v[74:75], v[78:79]
	v_pk_mul_f32 v[80:81], v[80:81], v[94:95]
	s_nop 0
	v_cndmask_b32_e64 v80, v80, -v80, s[40:41]
	v_cndmask_b32_e64 v81, v81, -v81, s[40:41]
	v_pk_fma_f32 v[44:45], v[44:45], v[76:77], v[80:81]
.LBB0_390:
	s_or_b64 exec, exec, s[14:15]
	v_mul_f32_e32 v50, 0x3e38aa3b, v50
	v_mul_f32_e32 v47, 0x3e38aa3b, v47
	v_mul_f32_e32 v58, 0x3e38aa3b, v58
	v_mul_f32_e32 v59, 0x3e38aa3b, v59
	v_mul_f32_e32 v56, 0x3e38aa3b, v56
	v_mul_f32_e32 v57, 0x3e38aa3b, v57
	v_mul_f32_e32 v54, 0x3e38aa3b, v54
	v_mul_f32_e32 v55, 0x3e38aa3b, v55
	v_mul_f32_e32 v52, 0x3e38aa3b, v52
	v_mul_f32_e32 v53, 0x3e38aa3b, v53
	v_mul_f32_e32 v51, 0x3e38aa3b, v51
	v_mul_f32_e32 v61, 0x3e38aa3b, v48
	v_mul_f32_e32 v49, 0x3e38aa3b, v49
	v_mul_f32_e32 v62, 0x3e38aa3b, v46
	v_mul_f32_e32 v63, 0x3e38aa3b, v44
	v_mul_f32_e32 v64, 0x3e38aa3b, v45
	s_nop 1
	v_cvt_pk_bf16_f32 v44, v58, v59
	s_nop 1
	v_cvt_pk_bf16_f32 v48, v50, v51
	s_nop 1
	v_cvt_pk_bf16_f32 v45, v56, v57
	s_nop 1
	v_cvt_pk_bf16_f32 v46, v54, v55
	s_nop 1
	v_cvt_pk_bf16_f32 v50, v62, v47
	s_nop 1
	v_cvt_pk_bf16_f32 v47, v52, v53
	s_nop 1
	v_cvt_pk_bf16_f32 v49, v61, v49
	s_nop 1
	v_cvt_pk_bf16_f32 v51, v63, v64
	global_store_dwordx4 v[42:43], v[44:47], off
	global_store_dwordx4 v[42:43], v[48:51], off offset:16
	v_lshl_add_u64 v[40:41], v[38:39], 0, v[40:41]
	s_waitcnt vmcnt(6)
	s_nop 1
	v_mov_b32_e32 v42, v108
	v_mov_b32_e32 v43, v109
	v_mov_b32_e32 v44, v110
	v_mov_b32_e32 v45, v111
	v_mov_b32_e32 v46, v112
	v_mov_b32_e32 v47, v113
	v_mov_b32_e32 v48, v114
	v_mov_b32_e32 v49, v115
	v_lshl_add_u64 v[96:97], s[100:101], 0, v[40:41]
	global_load_dwordx4 v[108:111], v[96:97], off offset:16
	global_load_dwordx4 v[112:115], v[96:97], off
	v_lshlrev_b32_e32 v68, 16, v42
	v_lshlrev_b32_e32 v52, 16, v46
	v_and_b32_e32 v53, 0xffff0000, v46
	v_pk_mul_f32 v[54:55], v[52:53], v[52:53]
	v_lshlrev_b32_e32 v46, 16, v47
	v_and_b32_e32 v47, 0xffff0000, v47
	v_pk_mul_f32 v[58:59], v[46:47], v[46:47]
	v_add_f32_e32 v54, v54, v55
	v_lshlrev_b32_e32 v62, 16, v48
	v_and_b32_e32 v63, 0xffff0000, v48
	v_add_f32_e32 v54, v58, v54
	v_pk_mul_f32 v[64:65], v[62:63], v[62:63]
	v_add_f32_e32 v54, v59, v54
	v_lshlrev_b32_e32 v48, 16, v49
	v_and_b32_e32 v49, 0xffff0000, v49
	v_add_f32_e32 v54, v64, v54
	v_pk_mul_f32 v[66:67], v[48:49], v[48:49]
	v_add_f32_e32 v54, v65, v54
	v_and_b32_e32 v69, 0xffff0000, v42
	v_add_f32_e32 v54, v66, v54
	v_pk_mul_f32 v[70:71], v[68:69], v[68:69]
	v_add_f32_e32 v54, v67, v54
	v_lshlrev_b32_e32 v72, 16, v43
	v_and_b32_e32 v73, 0xffff0000, v43
	v_add_f32_e32 v54, v70, v54
	v_pk_mul_f32 v[42:43], v[72:73], v[72:73]
	v_add_f32_e32 v54, v71, v54
	v_lshlrev_b32_e32 v74, 16, v44
	v_and_b32_e32 v75, 0xffff0000, v44
	v_add_f32_e32 v42, v42, v54
	v_and_b32_e32 v56, 0xffff0000, v45
	v_lshlrev_b32_e32 v57, 16, v45
	v_pk_mul_f32 v[44:45], v[74:75], v[74:75]
	v_add_f32_e32 v42, v43, v42
	v_add_f32_e32 v42, v44, v42
	v_pk_mul_f32 v[50:51], v[56:57], v[56:57]
	v_add_f32_e32 v42, v45, v42
	v_add_f32_e32 v42, v51, v42
	v_add_f32_e32 v42, v50, v42
	s_nop 1
	v_mov_b32_dpp v43, v42 quad_perm:[1,0,3,2] row_mask:0xf bank_mask:0xf
	v_add_f32_e32 v42, v42, v43
	s_nop 1
	v_mov_b32_dpp v43, v42 quad_perm:[2,3,0,1] row_mask:0xf bank_mask:0xf
	v_add_f32_e32 v42, v42, v43
	v_fmamk_f32 v42, v42, 0x3c800000, v234
	v_cmp_gt_f32_e64 s[44:45], s90, v42
	v_mul_f32_e32 v43, 0x4b800000, v42
	s_nop 0
	v_cndmask_b32_e64 v42, v42, v43, s[44:45]
	v_rsq_f32_e32 v42, v42
	s_nop 0
	v_mul_f32_e32 v43, 0x45800000, v42
	v_cndmask_b32_e64 v58, v42, v43, s[44:45]
	v_pk_mul_f32 v[42:43], v[58:59], v[52:53] op_sel_hi:[0,1]
	v_pk_mul_f32 v[44:45], v[58:59], v[46:47] op_sel_hi:[0,1]
	v_pk_mul_f32 v[46:47], v[58:59], v[62:63] op_sel_hi:[0,1]
	v_pk_mul_f32 v[48:49], v[58:59], v[48:49] op_sel_hi:[0,1]
	v_pk_mul_f32 v[50:51], v[58:59], v[68:69] op_sel_hi:[0,1]
	v_pk_mul_f32 v[52:53], v[58:59], v[72:73] op_sel_hi:[0,1]
	v_pk_mul_f32 v[54:55], v[58:59], v[74:75] op_sel_hi:[0,1]
	v_pk_mul_f32 v[56:57], v[58:59], v[56:57] op_sel_hi:[0,1]
	v_pk_mul_f32 v[42:43], v[14:15], v[42:43]
	v_pk_mul_f32 v[44:45], v[16:17], v[44:45]
	v_pk_mul_f32 v[46:47], v[10:11], v[46:47]
	v_pk_mul_f32 v[48:49], v[12:13], v[48:49]
	v_pk_mul_f32 v[50:51], v[6:7], v[50:51]
	v_pk_mul_f32 v[52:53], v[8:9], v[52:53]
	v_pk_mul_f32 v[54:55], v[2:3], v[54:55]
	v_pk_mul_f32 v[56:57], v[4:5], v[56:57] op_sel:[0,1] op_sel_hi:[1,0]
	s_and_saveexec_b64 s[14:15], s[42:43]
	s_cbranch_execz .LBB0_387
	v_mov_b32_dpp v58, v42 quad_perm:[1,0,3,2] row_mask:0xf bank_mask:0xf
	v_mov_b32_dpp v59, v43 quad_perm:[1,0,3,2] row_mask:0xf bank_mask:0xf
	ds_read_b128 v[62:65], v35
	ds_read_b128 v[66:69], v35 offset:16
	ds_read_b128 v[70:73], v35 offset:32
	ds_read_b128 v[74:77], v35 offset:48
	ds_read_b128 v[78:81], v35 offset:4096
	v_mov_b32_dpp v84, v46 quad_perm:[1,0,3,2] row_mask:0xf bank_mask:0xf
	v_mov_b32_dpp v85, v47 quad_perm:[1,0,3,2] row_mask:0xf bank_mask:0xf
	v_mov_b32_dpp v88, v50 quad_perm:[1,0,3,2] row_mask:0xf bank_mask:0xf
	v_mov_b32_dpp v89, v51 quad_perm:[1,0,3,2] row_mask:0xf bank_mask:0xf
	s_waitcnt lgkmcnt(0)
	v_pk_mul_f32 v[58:59], v[78:79], v[58:59]
	v_mov_b32_dpp v78, v44 quad_perm:[1,0,3,2] row_mask:0xf bank_mask:0xf
	v_mov_b32_dpp v79, v45 quad_perm:[1,0,3,2] row_mask:0xf bank_mask:0xf
	v_mov_b32_dpp v92, v54 quad_perm:[1,0,3,2] row_mask:0xf bank_mask:0xf
	v_mov_b32_dpp v93, v55 quad_perm:[1,0,3,2] row_mask:0xf bank_mask:0xf
	v_cndmask_b32_e64 v59, v59, -v59, s[40:41]
	v_cndmask_b32_e64 v58, v58, -v58, s[40:41]
	v_pk_mul_f32 v[82:83], v[80:81], v[78:79]
	ds_read_b128 v[78:81], v35 offset:4112
	v_cndmask_b32_e64 v83, v83, -v83, s[40:41]
	v_cndmask_b32_e64 v82, v82, -v82, s[40:41]
	v_pk_fma_f32 v[44:45], v[44:45], v[64:65], v[82:83]
	v_pk_fma_f32 v[42:43], v[42:43], v[62:63], v[58:59]
	s_waitcnt lgkmcnt(0)
	v_pk_mul_f32 v[84:85], v[78:79], v[84:85]
	v_mov_b32_dpp v78, v48 quad_perm:[1,0,3,2] row_mask:0xf bank_mask:0xf
	v_mov_b32_dpp v79, v49 quad_perm:[1,0,3,2] row_mask:0xf bank_mask:0xf
	v_cndmask_b32_e64 v85, v85, -v85, s[40:41]
	v_cndmask_b32_e64 v84, v84, -v84, s[40:41]
	v_pk_fma_f32 v[46:47], v[46:47], v[66:67], v[84:85]
	v_pk_mul_f32 v[86:87], v[80:81], v[78:79]
	ds_read_b128 v[78:81], v35 offset:4128
	v_cndmask_b32_e64 v86, v86, -v86, s[40:41]
	v_cndmask_b32_e64 v87, v87, -v87, s[40:41]
	v_pk_fma_f32 v[48:49], v[48:49], v[68:69], v[86:87]
	s_waitcnt lgkmcnt(0)
	v_pk_mul_f32 v[88:89], v[78:79], v[88:89]
	v_mov_b32_dpp v78, v52 quad_perm:[1,0,3,2] row_mask:0xf bank_mask:0xf
	v_mov_b32_dpp v79, v53 quad_perm:[1,0,3,2] row_mask:0xf bank_mask:0xf
	v_cndmask_b32_e64 v88, v88, -v88, s[40:41]
	v_cndmask_b32_e64 v89, v89, -v89, s[40:41]
	v_pk_fma_f32 v[50:51], v[50:51], v[70:71], v[88:89]
	v_pk_mul_f32 v[90:91], v[80:81], v[78:79]
	ds_read_b128 v[78:81], v35 offset:4144
	v_cndmask_b32_e64 v90, v90, -v90, s[40:41]
	v_cndmask_b32_e64 v91, v91, -v91, s[40:41]
	v_pk_fma_f32 v[52:53], v[52:53], v[72:73], v[90:91]
	s_waitcnt lgkmcnt(0)
	v_pk_mul_f32 v[78:79], v[78:79], v[92:93]
	v_mov_b32_dpp v92, v56 quad_perm:[1,0,3,2] row_mask:0xf bank_mask:0xf
	v_mov_b32_dpp v93, v57 quad_perm:[1,0,3,2] row_mask:0xf bank_mask:0xf
	v_cndmask_b32_e64 v78, v78, -v78, s[40:41]
	v_cndmask_b32_e64 v79, v79, -v79, s[40:41]
	v_pk_fma_f32 v[54:55], v[54:55], v[74:75], v[78:79]
	v_pk_mul_f32 v[80:81], v[80:81], v[92:93]
	s_nop 0
	v_cndmask_b32_e64 v80, v80, -v80, s[40:41]
	v_cndmask_b32_e64 v81, v81, -v81, s[40:41]
	v_pk_fma_f32 v[56:57], v[56:57], v[76:77], v[80:81]
	s_branch .LBB0_387
